# ml_conv: per-token 64-lane gate-sum tree via v_permlane32/16_swap + DPP adds instead of 10 ds_bpermute round trips
# baseline (speedup 1.0000x reference)
.LBB0_603:
	v_lshlrev_b32_e32 v208, 16, v174
	v_and_b32_e32 v210, 0xffff0000, v174
	v_lshlrev_b32_e32 v212, 16, v175
	v_and_b32_e32 v214, 0xffff0000, v175
	v_pk_mul_f32 v[174:175], v[14:15], v[192:193]
	v_lshlrev_b32_e32 v216, 16, v176
	v_add_f32_e32 v174, v10, v174
	v_and_b32_e32 v218, 0xffff0000, v176
	v_add_f32_e32 v176, v174, v175
	v_pk_mul_f32 v[174:175], v[34:35], v[208:209]
	v_lshlrev_b32_e32 v220, 16, v177
	v_add_f32_e32 v175, v175, v176
	v_add_f32_e32 v174, v174, v175
	v_mul_f32_e32 v175, 0xbfb8aa3b, v174
	v_exp_f32_e32 v175, v175
	v_and_b32_e32 v222, 0xffff0000, v177
	v_pk_mul_f32 v[176:177], v[18:19], v[194:195]
	v_pk_mul_f32 v[186:187], v[16:17], v[196:197]
	v_add_f32_e32 v175, 1.0, v175
	v_rcp_f32_e32 v175, v175
	s_nop 0
	v_mul_f32_e32 v174, v174, v175
	v_add_f32_e32 v175, v11, v176
	v_add_f32_e32 v175, v175, v177
	v_pk_mul_f32 v[176:177], v[26:27], v[210:211]
	s_nop 0
	v_add_f32_e32 v175, v177, v175
	v_add_f32_e32 v175, v176, v175
	v_mul_f32_e32 v176, 0xbfb8aa3b, v175
	v_exp_f32_e32 v176, v176
	s_nop 0
	v_add_f32_e32 v176, 1.0, v176
	v_rcp_f32_e32 v176, v176
	s_nop 0
	v_mul_f32_e32 v176, v175, v176
	v_add_f32_e32 v175, v12, v186
	v_add_f32_e32 v175, v175, v187
	v_pk_mul_f32 v[186:187], v[36:37], v[212:213]
	s_nop 0
	v_add_f32_e32 v175, v187, v175
	v_add_f32_e32 v175, v186, v175
	v_mul_f32_e32 v177, 0xbfb8aa3b, v175
	v_exp_f32_e32 v177, v177
	v_pk_mul_f32 v[186:187], v[20:21], v[198:199]
	v_add_f32_e32 v177, 1.0, v177
	v_rcp_f32_e32 v177, v177
	s_nop 0
	v_mul_f32_e32 v192, v175, v177
	v_add_f32_e32 v175, v13, v186
	v_add_f32_e32 v175, v175, v187
	v_pk_mul_f32 v[186:187], v[28:29], v[214:215]
	s_nop 0
	v_add_f32_e32 v175, v187, v175
	v_add_f32_e32 v175, v186, v175
	v_mul_f32_e32 v177, 0xbfb8aa3b, v175
	v_exp_f32_e32 v177, v177
	v_pk_mul_f32 v[186:187], v[6:7], v[200:201]
	v_add_f32_e32 v177, 1.0, v177
	v_rcp_f32_e32 v177, v177
	s_nop 0
	v_mul_f32_e32 v194, v175, v177
	v_add_f32_e32 v175, v2, v186
	v_add_f32_e32 v175, v175, v187
	v_pk_mul_f32 v[186:187], v[38:39], v[216:217]
	s_nop 0
	v_add_f32_e32 v175, v187, v175
	v_add_f32_e32 v175, v186, v175
	v_mul_f32_e32 v177, 0xbfb8aa3b, v175
	v_exp_f32_e32 v177, v177
	v_pk_mul_f32 v[186:187], v[22:23], v[202:203]
	v_add_f32_e32 v177, 1.0, v177
	v_rcp_f32_e32 v177, v177
	s_nop 0
	v_mul_f32_e32 v196, v175, v177
	v_add_f32_e32 v175, v3, v186
	v_add_f32_e32 v175, v175, v187
	v_pk_mul_f32 v[186:187], v[30:31], v[218:219]
	s_nop 0
	v_add_f32_e32 v175, v187, v175
	v_add_f32_e32 v175, v186, v175
	v_mul_f32_e32 v177, 0xbfb8aa3b, v175
	v_exp_f32_e32 v177, v177
	v_pk_mul_f32 v[186:187], v[8:9], v[204:205]
	v_add_f32_e32 v177, 1.0, v177
	v_rcp_f32_e32 v177, v177
	s_nop 0
	v_mul_f32_e32 v198, v175, v177
	v_add_f32_e32 v175, v4, v186
	v_add_f32_e32 v175, v175, v187
	v_pk_mul_f32 v[186:187], v[40:41], v[220:221]
	v_cvt_pk_bf16_f32 v188, v196, v198
	v_add_f32_e32 v175, v187, v175
	v_add_f32_e32 v175, v186, v175
	v_mul_f32_e32 v177, 0xbfb8aa3b, v175
	v_exp_f32_e32 v177, v177
	v_pk_mul_f32 v[186:187], v[24:25], v[206:207]
	v_add_f32_e32 v177, 1.0, v177
	v_rcp_f32_e32 v177, v177
	s_nop 0
	v_mul_f32_e32 v200, v175, v177
	v_add_f32_e32 v175, v5, v186
	v_add_f32_e32 v175, v175, v187
	v_pk_mul_f32 v[186:187], v[32:33], v[222:223]
	s_nop 0
	v_add_f32_e32 v175, v187, v175
	v_add_f32_e32 v175, v186, v175
	v_mul_f32_e32 v177, 0xbfb8aa3b, v175
	v_exp_f32_e32 v177, v177
	v_cvt_pk_bf16_f32 v186, v174, v176
	v_cvt_pk_bf16_f32 v187, v192, v194
	v_pk_fma_f32 v[230:231], v[50:51], v[174:175], 0 op_sel_hi:[1,0,0]
	v_add_f32_e32 v177, 1.0, v177
	v_rcp_f32_e32 v177, v177
	v_pk_fma_f32 v[230:231], v[70:71], v[208:209], v[230:231] op_sel_hi:[1,0,1]
	v_mul_f32_e32 v202, v175, v177
	v_cvt_pk_bf16_f32 v189, v200, v202
	global_store_dwordx4 v[228:229], v[186:189], off
	v_pk_fma_f32 v[230:231], v[42:43], v[176:177], v[230:231] op_sel_hi:[1,0,1]
	s_nop 0
	v_pk_fma_f32 v[186:187], v[54:55], v[174:175], 0 op_sel_hi:[1,0,0]
	v_pk_fma_f32 v[230:231], v[62:63], v[210:211], v[230:231] op_sel_hi:[1,0,1]
	v_pk_fma_f32 v[186:187], v[58:59], v[208:209], v[186:187] op_sel_hi:[1,0,1]
	v_pk_fma_f32 v[230:231], v[82:83], v[192:193], v[230:231] op_sel_hi:[1,0,1]
	v_pk_fma_f32 v[186:187], v[46:47], v[176:177], v[186:187] op_sel_hi:[1,0,1]
	v_pk_fma_f32 v[230:231], v[102:103], v[212:213], v[230:231] op_sel_hi:[1,0,1]
	v_pk_fma_f32 v[186:187], v[66:67], v[210:211], v[186:187] op_sel_hi:[1,0,1]
	v_pk_fma_f32 v[230:231], v[74:75], v[194:195], v[230:231] op_sel_hi:[1,0,1]
	v_pk_fma_f32 v[186:187], v[86:87], v[192:193], v[186:187] op_sel_hi:[1,0,1]
	v_pk_fma_f32 v[230:231], v[94:95], v[214:215], v[230:231] op_sel_hi:[1,0,1]
	v_pk_fma_f32 v[186:187], v[90:91], v[212:213], v[186:187] op_sel_hi:[1,0,1]
	v_pk_fma_f32 v[230:231], v[114:115], v[196:197], v[230:231] op_sel_hi:[1,0,1]
	v_pk_fma_f32 v[186:187], v[78:79], v[194:195], v[186:187] op_sel_hi:[1,0,1]
	v_pk_fma_f32 v[230:231], v[134:135], v[216:217], v[230:231] op_sel_hi:[1,0,1]
	v_pk_fma_f32 v[186:187], v[98:99], v[214:215], v[186:187] op_sel_hi:[1,0,1]
	v_pk_fma_f32 v[230:231], v[106:107], v[198:199], v[230:231] op_sel_hi:[1,0,1]
	v_pk_fma_f32 v[186:187], v[118:119], v[196:197], v[186:187] op_sel_hi:[1,0,1]
	v_pk_fma_f32 v[230:231], v[126:127], v[218:219], v[230:231] op_sel_hi:[1,0,1]
	v_pk_fma_f32 v[186:187], v[122:123], v[216:217], v[186:187] op_sel_hi:[1,0,1]
	v_pk_fma_f32 v[188:189], v[56:57], v[174:175], 0 op_sel_hi:[1,0,0]
	v_pk_fma_f32 v[186:187], v[110:111], v[198:199], v[186:187] op_sel_hi:[1,0,1]
	v_pk_fma_f32 v[230:231], v[146:147], v[200:201], v[230:231] op_sel_hi:[1,0,1]
	v_pk_fma_f32 v[186:187], v[130:131], v[218:219], v[186:187] op_sel_hi:[1,0,1]
	v_pk_fma_f32 v[174:175], v[52:53], v[174:175], 0 op_sel_hi:[1,0,0]
	v_pk_fma_f32 v[186:187], v[150:151], v[200:201], v[186:187] op_sel_hi:[1,0,1]
	v_pk_fma_f32 v[188:189], v[60:61], v[208:209], v[188:189] op_sel_hi:[1,0,1]
	v_pk_fma_f32 v[186:187], v[154:155], v[220:221], v[186:187] op_sel_hi:[1,0,1]
	v_pk_fma_f32 v[230:231], v[166:167], v[220:221], v[230:231] op_sel_hi:[1,0,1]
	v_pk_fma_f32 v[174:175], v[72:73], v[208:209], v[174:175] op_sel_hi:[1,0,1]
	v_pk_fma_f32 v[186:187], v[142:143], v[202:203], v[186:187] op_sel_hi:[1,0,1]
	v_pk_fma_f32 v[188:189], v[48:49], v[176:177], v[188:189] op_sel_hi:[1,0,1]
	v_pk_fma_f32 v[230:231], v[138:139], v[202:203], v[230:231] op_sel_hi:[1,0,1]
	v_pk_fma_f32 v[174:175], v[44:45], v[176:177], v[174:175] op_sel_hi:[1,0,1]
	v_pk_fma_f32 v[186:187], v[162:163], v[222:223], v[186:187] op_sel_hi:[1,0,1]
	v_pk_fma_f32 v[188:189], v[68:69], v[210:211], v[188:189] op_sel_hi:[1,0,1]
	v_pk_fma_f32 v[230:231], v[158:159], v[222:223], v[230:231] op_sel_hi:[1,0,1]
	v_pk_fma_f32 v[174:175], v[64:65], v[210:211], v[174:175] op_sel_hi:[1,0,1]
	v_pk_fma_f32 v[188:189], v[88:89], v[192:193], v[188:189] op_sel_hi:[1,0,1]
	v_pk_fma_f32 v[174:175], v[84:85], v[192:193], v[174:175] op_sel_hi:[1,0,1]
	v_pk_fma_f32 v[188:189], v[92:93], v[212:213], v[188:189] op_sel_hi:[1,0,1]
	v_pk_fma_f32 v[174:175], v[104:105], v[212:213], v[174:175] op_sel_hi:[1,0,1]
	v_pk_fma_f32 v[188:189], v[80:81], v[194:195], v[188:189] op_sel_hi:[1,0,1]
	v_pk_fma_f32 v[174:175], v[76:77], v[194:195], v[174:175] op_sel_hi:[1,0,1]
	v_pk_fma_f32 v[188:189], v[100:101], v[214:215], v[188:189] op_sel_hi:[1,0,1]
	v_pk_fma_f32 v[174:175], v[96:97], v[214:215], v[174:175] op_sel_hi:[1,0,1]
	v_pk_fma_f32 v[188:189], v[120:121], v[196:197], v[188:189] op_sel_hi:[1,0,1]
	v_pk_fma_f32 v[174:175], v[116:117], v[196:197], v[174:175] op_sel_hi:[1,0,1]
	v_pk_fma_f32 v[188:189], v[124:125], v[216:217], v[188:189] op_sel_hi:[1,0,1]
	v_pk_fma_f32 v[174:175], v[136:137], v[216:217], v[174:175] op_sel_hi:[1,0,1]
	v_pk_fma_f32 v[188:189], v[112:113], v[198:199], v[188:189] op_sel_hi:[1,0,1]
	v_pk_fma_f32 v[174:175], v[108:109], v[198:199], v[174:175] op_sel_hi:[1,0,1]
	v_pk_fma_f32 v[188:189], v[132:133], v[218:219], v[188:189] op_sel_hi:[1,0,1]
	v_pk_fma_f32 v[174:175], v[128:129], v[218:219], v[174:175] op_sel_hi:[1,0,1]
	v_pk_fma_f32 v[188:189], v[152:153], v[200:201], v[188:189] op_sel_hi:[1,0,1]
	v_pk_fma_f32 v[174:175], v[148:149], v[200:201], v[174:175] op_sel_hi:[1,0,1]
	v_pk_fma_f32 v[188:189], v[156:157], v[220:221], v[188:189] op_sel_hi:[1,0,1]
	v_pk_fma_f32 v[174:175], v[168:169], v[220:221], v[174:175] op_sel_hi:[1,0,1]
	v_pk_fma_f32 v[188:189], v[144:145], v[202:203], v[188:189] op_sel_hi:[1,0,1]
	v_pk_fma_f32 v[174:175], v[140:141], v[202:203], v[174:175] op_sel_hi:[1,0,1]
	v_pk_fma_f32 v[188:189], v[164:165], v[222:223], v[188:189] op_sel_hi:[1,0,1]
	v_pk_fma_f32 v[174:175], v[160:161], v[222:223], v[174:175] op_sel_hi:[1,0,1]
	s_nop 1
	v_permlane32_swap_b32 v186, v230
	v_permlane32_swap_b32 v187, v231
	v_permlane32_swap_b32 v188, v174
	v_permlane32_swap_b32 v189, v175
	v_add_f32_e32 v176, v186, v230
	v_add_f32_e32 v177, v187, v231
	v_add_f32_e32 v174, v188, v174
	v_add_f32_e32 v175, v189, v175
	s_nop 1
	v_permlane16_swap_b32 v176, v174
	v_permlane16_swap_b32 v177, v175
	v_add_f32_e32 v174, v176, v174
	v_add_f32_e32 v175, v177, v175
	v_cndmask_b32_e64 v176, v174, v175, s[6:7]
	v_cndmask_b32_e64 v174, v175, v174, s[6:7]
	s_nop 1
	v_add_f32_dpp v174, v176, v174 row_ror:8 row_mask:0xf bank_mask:0xf
	s_nop 1
	v_add_f32_dpp v174, v174, v174 quad_perm:[1,0,3,2] row_mask:0xf bank_mask:0xf
	s_nop 1
	v_add_f32_dpp v174, v174, v174 quad_perm:[2,3,0,1] row_mask:0xf bank_mask:0xf
	s_nop 1
	v_add_f32_dpp v174, v174, v174 row_half_mirror row_mask:0xf bank_mask:0xf
	s_and_saveexec_b64 s[2:3], s[8:9]
	s_cbranch_execz .LBB0_598
	global_store_dword v[226:227], v174, off
	s_branch .LBB0_598
